# out GEMM K-loop: same hand-written software-pipelined two-staging-set loop as proj
# baseline (speedup 1.0000x reference)
; DI f32x16 zero16() { f32x16 z; _Pragma("unroll") for (int i = 0; i < 16; ++i) z[i] = 0.f; return z; }
; #define G_LOAD(KOFF) do { rw0 = *(const uint4*)(gw + (KOFF)); rw1 = *(const uint4*)(gw1 + (KOFF)); rw2 = *(const uint4*)(gw2 + (KOFF)); rw3 = *(const uint4*)(gw3 + (KOFF)); \
;                           rx0 = *(const uint4*)(gx + (KOFF)); rx1 = *(const uint4*)(gx1 + (KOFF)); rx2 = *(const uint4*)(gx2 + (KOFF)); rx3 = *(const uint4*)(gx3 + (KOFF)); } while (0)
; DI void gemm128(const u16* __restrict__ W, int ldw, const u16* __restrict__ X, int ldx, int K, f32x16 (&acc)[2][2], char* smem) {
;     ...
;   const u16* gw = W + (size_t)lr * ldw + lc * 8;
;   const u16* gx = X + (size_t)lr * ldx + lc * 8;
;   const u16* gw1 = gw + (size_t)32 * ldw; const u16* gw2 = gw + (size_t)64 * ldw; const u16* gw3 = gw + (size_t)96 * ldw;
;   const u16* gx1 = gx + (size_t)32 * ldx; const u16* gx2 = gx + (size_t)64 * ldx; const u16* gx3 = gx + (size_t)96 * ldx;
;   uint4 rw0, rw1, rw2, rw3, rx0, rx1, rx2, rx3;
;     ...
;   G_LOAD(0);
;   G_STORE(0);
;   const int nk = K >> 6;
;   G_LOAD(64);
;   __syncthreads();
; DI void phase_out(const Params& p, int layer, char* smem, int xcd, int loc, int nloc) {
;     ...
;   for (int i = loc;; i += nloc) {
;     int mt, nt;
;     if (!tile_order<8>(i, xcd, mt, nt)) break;
;     const int m0 = mt * 128, n0 = nt * 128;
;     f32x16 acc[2][2];
;     acc[0][0] = zero16(); acc[0][1] = zero16(); acc[1][0] = zero16(); acc[1][1] = zero16();
;     gemm128(WOUT + (size_t)n0 * LDX, LDX, MG + (size_t)m0 * LDX, LDX, 1024, acc, smem);
.LBB0_1400:
	s_ashr_i32 s1, s28, 31
	s_lshr_b32 s1, s1, 26
	s_add_i32 s1, s28, s1
	s_ashr_i32 s12, s1, 6
	s_andn2_b32 s1, s1, 63
	s_sub_i32 s1, s28, s1
	s_lshl_b32 s12, s12, 3
	s_ashr_i32 s44, s1, 3
	s_bfe_u32 s0, s28, 0x30003
	s_add_i32 s41, s12, s15
	s_and_b32 s12, s28, 7
	s_and_b32 s1, s44, -8
	s_or_b32 s12, s41, s12
	s_or_b32 s29, s1, s0
	s_and_b32 s37, s19, 7
	s_lshl_b32 s40, s0, 7
	s_lshl_b32 s31, s12, 7
	s_lshl_b32 s30, s29, 7
	s_mul_i32 s0, s29, 0x44000
	s_mul_hi_i32 s1, s30, 0x880
	s_add_u32 s0, s5, s0
	s_addc_u32 s1, s14, s1
	s_mul_i32 s12, s12, 0x44000
	v_mov_b32_e32 v52, v128
	s_mul_hi_i32 s13, s31, 0x880
	s_add_u32 s12, s20, s12
	s_waitcnt lgkmcnt(0)
	v_mov_b64_e32 v[0:1], s[0:1]
	v_ashrrev_i32_e32 v53, 3, v52
	v_lshlrev_b32_e32 v2, 4, v52
	s_addc_u32 s13, s21, s13
	v_mad_i64_i32 v[0:1], s[0:1], v53, s24, v[0:1]
	v_and_b32_e32 v2, 0x70, v2
	v_lshl_add_u64 v[36:37], v[0:1], 0, v[2:3]
	v_mov_b64_e32 v[0:1], s[12:13]
	v_mad_i64_i32 v[0:1], s[0:1], v53, s24, v[0:1]
	v_add_co_u32_e64 v40, s[0:1], s38, v36
	v_lshl_add_u64 v[38:39], v[0:1], 0, v[2:3]
	s_nop 0
	v_addc_co_u32_e64 v41, s[0:1], 0, v37, s[0:1]
	v_add_co_u32_e64 v42, s[0:1], s39, v36
	s_waitcnt lgkmcnt(0)
	global_load_dwordx4 v[4:7], v[36:37], off
	global_load_dwordx4 v[8:11], v[40:41], off
	v_addc_co_u32_e64 v43, s[0:1], 0, v37, s[0:1]
	v_add_co_u32_e64 v44, s[0:1], s42, v36
	global_load_dwordx4 v[12:15], v[42:43], off
	s_nop 0
	v_addc_co_u32_e64 v45, s[0:1], 0, v37, s[0:1]
	v_add_co_u32_e64 v46, s[0:1], s38, v38
	global_load_dwordx4 v[16:19], v[44:45], off
	global_load_dwordx4 v[20:23], v[38:39], off
	v_addc_co_u32_e64 v47, s[0:1], 0, v39, s[0:1]
	v_add_co_u32_e64 v48, s[0:1], s39, v38
	global_load_dwordx4 v[24:27], v[46:47], off
	s_nop 0
	v_addc_co_u32_e64 v49, s[0:1], 0, v39, s[0:1]
	v_add_co_u32_e64 v50, s[0:1], s42, v38
	global_load_dwordx4 v[28:31], v[48:49], off
	s_nop 0
	v_addc_co_u32_e64 v51, s[0:1], 0, v39, s[0:1]
	global_load_dwordx4 v[32:35], v[50:51], off
	global_load_dwordx4 v[68:71], v[36:37], off offset:128
	global_load_dwordx4 v[72:75], v[40:41], off offset:128
	global_load_dwordx4 v[76:79], v[42:43], off offset:128
	global_load_dwordx4 v[80:83], v[44:45], off offset:128
	global_load_dwordx4 v[84:87], v[38:39], off offset:128
	global_load_dwordx4 v[88:91], v[46:47], off offset:128
	global_load_dwordx4 v[92:95], v[48:49], off offset:128
	global_load_dwordx4 v[96:99], v[50:51], off offset:128
	v_mov_b64_e32 v[178:179], v[36:37]
	v_mov_b64_e32 v[180:181], v[40:41]
	v_mov_b64_e32 v[182:183], v[42:43]
	v_mov_b64_e32 v[184:185], v[44:45]
	v_mov_b64_e32 v[186:187], v[38:39]
	v_mov_b64_e32 v[188:189], v[46:47]
	v_mov_b64_e32 v[190:191], v[48:49]
	v_mov_b64_e32 v[192:193], v[50:51]
	v_and_b32_e32 v0, 31, v52
	v_readfirstlane_b32 s12, v52
	v_mul_u32_u24_e32 v54, 0x90, v0
	v_mad_u64_u32 v[0:1], s[0:1], v53, s2, v[2:3]
	s_and_b32 s0, s12, 64
	s_lshr_b32 s1, s12, 1
	v_lshrrev_b32_e32 v1, 1, v52
	s_mulk_i32 s0, 0x90
	s_and_b32 s1, s1, 0xfffffc0
	v_and_b32_e32 v1, 16, v1
	s_mulk_i32 s1, 0x90
	v_add3_u32 v106, s0, v54, v1
	s_add_i32 s0, s41, s37
	v_add3_u32 v1, s1, v54, v1
	s_lshl_b32 s1, s0, 7
	s_mul_i32 s0, s0, 0x44000
	s_mul_hi_i32 s1, s1, 0x880
	s_mov_b32 s36, 0
	s_mov_b64 s[12:13], 0
	s_waitcnt vmcnt(15)
	ds_write_b128 v0, v[4:7]
	s_waitcnt vmcnt(14)
	ds_write_b128 v0, v[8:11] offset:4608
	s_waitcnt vmcnt(13)
	ds_write_b128 v0, v[12:15] offset:9216
	s_waitcnt vmcnt(12)
	ds_write_b128 v0, v[16:19] offset:13824
	s_waitcnt vmcnt(11)
	ds_write_b128 v0, v[20:23] offset:36864
	s_waitcnt vmcnt(10)
	ds_write_b128 v0, v[24:27] offset:41472
	s_waitcnt vmcnt(9)
	ds_write_b128 v0, v[28:31] offset:46080
	s_waitcnt vmcnt(8)
	ds_write_b128 v0, v[32:35] offset:50688
	v_mov_b32_e32 v4, s0
	v_mov_b32_e32 v5, s1
	v_mad_i64_i32 v[4:5], s[0:1], v53, s24, v[4:5]
	s_lshl_b32 s0, s44, 7
	s_and_b32 s0, s0, 0xfffffc00
	s_or_b32 s0, s0, s40
	v_or_b32_e32 v4, v4, v2
	s_mul_hi_i32 s1, s0, 0x880
	s_mulk_i32 s0, 0x880
	v_lshl_add_u64 v[100:101], s[94:95], 0, v[4:5]
	v_mov_b32_e32 v4, s0
	v_mov_b32_e32 v5, s1
	v_mad_i64_i32 v[4:5], s[0:1], v53, s24, v[4:5]
	v_or_b32_e32 v4, v4, v2
	v_lshl_add_u64 v[102:103], s[6:7], 0, v[4:5]
	v_mov_b32_e32 v4, 0
	v_mov_b32_e32 v5, v4
	v_mov_b32_e32 v6, v4
	v_mov_b32_e32 v7, v4
	v_mov_b32_e32 v8, v4
	v_mov_b32_e32 v9, v4
	v_mov_b32_e32 v10, v4
	v_mov_b32_e32 v11, v4
	v_mov_b32_e32 v12, v4
	v_mov_b32_e32 v13, v4
	v_mov_b32_e32 v14, v4
	v_mov_b32_e32 v15, v4
	v_mov_b32_e32 v16, v4
	v_mov_b32_e32 v17, v4
	v_mov_b32_e32 v18, v4
	v_mov_b32_e32 v19, v4
	v_mov_b32_e32 v36, v4
	v_mov_b32_e32 v37, v4
	v_mov_b32_e32 v38, v4
	v_mov_b32_e32 v39, v4
	v_mov_b32_e32 v40, v4
	v_mov_b32_e32 v41, v4
	v_mov_b32_e32 v42, v4
	v_mov_b32_e32 v43, v4
	v_mov_b32_e32 v44, v4
	v_mov_b32_e32 v45, v4
	v_mov_b32_e32 v46, v4
	v_mov_b32_e32 v47, v4
	v_mov_b32_e32 v48, v4
	v_mov_b32_e32 v49, v4
	v_mov_b32_e32 v50, v4
	v_mov_b32_e32 v51, v4
	v_mov_b32_e32 v20, v4
	v_mov_b32_e32 v21, v4
	v_mov_b32_e32 v22, v4
	v_mov_b32_e32 v23, v4
	v_mov_b32_e32 v24, v4
	v_mov_b32_e32 v25, v4
	v_mov_b32_e32 v26, v4
	v_mov_b32_e32 v27, v4
	v_mov_b32_e32 v28, v4
	v_mov_b32_e32 v29, v4
	v_mov_b32_e32 v30, v4
	v_mov_b32_e32 v31, v4
	v_mov_b32_e32 v32, v4
	v_mov_b32_e32 v33, v4
	v_mov_b32_e32 v34, v4
	v_mov_b32_e32 v35, v4
	v_mov_b32_e32 v52, v4
	v_mov_b32_e32 v53, v4
	v_mov_b32_e32 v54, v4
	v_mov_b32_e32 v55, v4
	v_mov_b32_e32 v56, v4
	v_mov_b32_e32 v57, v4
	v_mov_b32_e32 v58, v4
	v_mov_b32_e32 v59, v4
	v_mov_b32_e32 v60, v4
	v_mov_b32_e32 v61, v4
	v_mov_b32_e32 v62, v4
	v_mov_b32_e32 v63, v4
	v_mov_b32_e32 v64, v4
	v_mov_b32_e32 v65, v4
	v_mov_b32_e32 v66, v4
	v_mov_b32_e32 v67, v4
	s_waitcnt lgkmcnt(0)
	s_barrier
	s_movk_i32 s12, 0x80
	s_mov_b32 s13, 0
	global_load_dwordx4 v[170:173], v[178:179], off offset:256
	global_load_dwordx4 v[174:177], v[180:181], off offset:256
	global_load_dwordx4 v[194:197], v[182:183], off offset:256
	global_load_dwordx4 v[198:201], v[184:185], off offset:256
	global_load_dwordx4 v[230:233], v[186:187], off offset:256
	global_load_dwordx4 v[240:243], v[188:189], off offset:256
	global_load_dwordx4 v[244:247], v[190:191], off offset:256
	global_load_dwordx4 v[248:251], v[192:193], off offset:256
	ds_read_b128 v[108:111], v106
	ds_read_b128 v[116:119], v1 offset:36864
	ds_read_b128 v[120:123], v1 offset:41472
	ds_read_b128 v[112:115], v106 offset:4608
; #define MFMA32(a, b, c) __builtin_amdgcn_mfma_f32_32x32x16_bf16((a), (b), (c), 0, 0, 0)
; #define G_LOAD(KOFF) do { rw0 = *(const uint4*)(gw + (KOFF)); rw1 = *(const uint4*)(gw1 + (KOFF)); rw2 = *(const uint4*)(gw2 + (KOFF)); rw3 = *(const uint4*)(gw3 + (KOFF)); \
;                           rx0 = *(const uint4*)(gx + (KOFF)); rx1 = *(const uint4*)(gx1 + (KOFF)); rx2 = *(const uint4*)(gx2 + (KOFF)); rx3 = *(const uint4*)(gx3 + (KOFF)); } while (0)
; DI void gemm128(const u16* __restrict__ W, int ldw, const u16* __restrict__ X, int ldx, int K, f32x16 (&acc)[2][2], char* smem) {
;     ...
;   for (int kt = 0; kt < nk; ++kt) {
;     const int buf = kt & 1;
; #pragma unroll
;     for (int ks = 0; ks < 4; ++ks) {
;       bf16x8 a0 = *(const bf16x8*)&sw[buf][wn * 64 + r][ks * 16 + h * 8];
;       bf16x8 a1 = *(const bf16x8*)&sw[buf][wn * 64 + 32 + r][ks * 16 + h * 8];
;       bf16x8 b0 = *(const bf16x8*)&sx[buf][wm * 64 + r][ks * 16 + h * 8];
;       bf16x8 b1 = *(const bf16x8*)&sx[buf][wm * 64 + 32 + r][ks * 16 + h * 8];
;       acc[0][0] = MFMA32(a0, b0, acc[0][0]);
;       acc[0][1] = MFMA32(a0, b1, acc[0][1]);
;       acc[1][0] = MFMA32(a1, b0, acc[1][0]);
;       acc[1][1] = MFMA32(a1, b1, acc[1][1]);
;     }
;     if (kt + 1 < nk) G_STORE(buf ^ 1);
;     if (kt + 2 < nk) G_LOAD((kt + 2) * 64);
;     __syncthreads();
;   }
.Lout_kloop:
	s_and_b32 s0, s36, 1
	s_mul_i32 s1, s0, 0x4800
	s_xor_b32 s0, s0, 1
	s_mulk_i32 s0, 0x4800
	v_add_u32_e32 v2, s1, v106
	v_add_u32_e32 v107, s1, v1
	v_add_u32_e32 v158, s0, v0
	v_add_u32_e32 v159, s0, v106
	v_add_u32_e32 v160, s0, v1
	ds_read_b128 v[124:127], v2 offset:32
	ds_read_b128 v[150:153], v107 offset:36896
	ds_read_b128 v[154:157], v107 offset:41504
	ds_read_b128 v[130:133], v2 offset:4640
	s_waitcnt lgkmcnt(6)
	v_mfma_f32_32x32x16_bf16 v[52:67], v[108:111], v[116:119], v[52:67]
	s_waitcnt vmcnt(8)
	ds_write_b128 v158, v[68:71]
	ds_write_b128 v158, v[72:75] offset:4608
	global_load_dwordx4 v[68:71], v[178:179], off offset:384
	global_load_dwordx4 v[72:75], v[180:181], off offset:384
	s_waitcnt lgkmcnt(7)
	v_mfma_f32_32x32x16_bf16 v[20:35], v[108:111], v[120:123], v[20:35]
	ds_write_b128 v158, v[76:79] offset:9216
	ds_write_b128 v158, v[80:83] offset:13824
	global_load_dwordx4 v[76:79], v[182:183], off offset:384
	global_load_dwordx4 v[80:83], v[184:185], off offset:384
	s_waitcnt lgkmcnt(8)
	v_mfma_f32_32x32x16_bf16 v[36:51], v[112:115], v[116:119], v[36:51]
	ds_write_b128 v158, v[84:87] offset:36864
	ds_write_b128 v158, v[88:91] offset:41472
	global_load_dwordx4 v[84:87], v[186:187], off offset:384
	global_load_dwordx4 v[88:91], v[188:189], off offset:384
	v_mfma_f32_32x32x16_bf16 v[4:19], v[112:115], v[120:123], v[4:19]
	ds_write_b128 v158, v[92:95] offset:46080
	ds_write_b128 v158, v[96:99] offset:50688
	global_load_dwordx4 v[92:95], v[190:191], off offset:384
	global_load_dwordx4 v[96:99], v[192:193], off offset:384
	ds_read_b128 v[108:111], v2 offset:64
	ds_read_b128 v[116:119], v107 offset:36928
	ds_read_b128 v[120:123], v107 offset:41536
	ds_read_b128 v[112:115], v2 offset:4672
	s_waitcnt lgkmcnt(14)
	v_mfma_f32_32x32x16_bf16 v[52:67], v[124:127], v[150:153], v[52:67]
	s_waitcnt lgkmcnt(13)
	v_mfma_f32_32x32x16_bf16 v[20:35], v[124:127], v[154:157], v[20:35]
	s_waitcnt lgkmcnt(12)
	v_mfma_f32_32x32x16_bf16 v[36:51], v[130:133], v[150:153], v[36:51]
	v_mfma_f32_32x32x16_bf16 v[4:19], v[130:133], v[154:157], v[4:19]
	ds_read_b128 v[124:127], v2 offset:96
	ds_read_b128 v[150:153], v107 offset:36960
	ds_read_b128 v[154:157], v107 offset:41568
	ds_read_b128 v[130:133], v2 offset:4704
	s_waitcnt lgkmcnt(6)
	v_mfma_f32_32x32x16_bf16 v[52:67], v[108:111], v[116:119], v[52:67]
	v_lshl_add_u64 v[178:179], v[178:179], 0, s[12:13]
	v_lshl_add_u64 v[180:181], v[180:181], 0, s[12:13]
	v_lshl_add_u64 v[182:183], v[182:183], 0, s[12:13]
	s_waitcnt lgkmcnt(5)
	v_mfma_f32_32x32x16_bf16 v[20:35], v[108:111], v[120:123], v[20:35]
	v_lshl_add_u64 v[184:185], v[184:185], 0, s[12:13]
	v_lshl_add_u64 v[186:187], v[186:187], 0, s[12:13]
	v_lshl_add_u64 v[188:189], v[188:189], 0, s[12:13]
	s_waitcnt lgkmcnt(4)
	v_mfma_f32_32x32x16_bf16 v[36:51], v[112:115], v[116:119], v[36:51]
	v_lshl_add_u64 v[190:191], v[190:191], 0, s[12:13]
	v_lshl_add_u64 v[192:193], v[192:193], 0, s[12:13]
	v_mfma_f32_32x32x16_bf16 v[4:19], v[112:115], v[120:123], v[4:19]
	s_add_i32 s36, s36, 1
	s_waitcnt lgkmcnt(0)
	s_barrier
	ds_read_b128 v[108:111], v159
	ds_read_b128 v[116:119], v160 offset:36864
	ds_read_b128 v[120:123], v160 offset:41472
	ds_read_b128 v[112:115], v159 offset:4608
	v_mfma_f32_32x32x16_bf16 v[52:67], v[124:127], v[150:153], v[52:67]
	v_mfma_f32_32x32x16_bf16 v[20:35], v[124:127], v[154:157], v[20:35]
	v_mfma_f32_32x32x16_bf16 v[36:51], v[130:133], v[150:153], v[36:51]
	v_mfma_f32_32x32x16_bf16 v[4:19], v[130:133], v[154:157], v[4:19]
	s_and_b32 s0, s36, 1
	s_mul_i32 s1, s0, 0x4800
	s_xor_b32 s0, s0, 1
	s_mulk_i32 s0, 0x4800
	v_add_u32_e32 v2, s1, v106
	v_add_u32_e32 v107, s1, v1
	v_add_u32_e32 v158, s0, v0
	v_add_u32_e32 v159, s0, v106
	v_add_u32_e32 v160, s0, v1
	ds_read_b128 v[124:127], v2 offset:32
	ds_read_b128 v[150:153], v107 offset:36896
	ds_read_b128 v[154:157], v107 offset:41504
	ds_read_b128 v[130:133], v2 offset:4640
	s_waitcnt lgkmcnt(6)
	v_mfma_f32_32x32x16_bf16 v[52:67], v[108:111], v[116:119], v[52:67]
	s_waitcnt vmcnt(8)
	ds_write_b128 v158, v[170:173]
	ds_write_b128 v158, v[174:177] offset:4608
	global_load_dwordx4 v[170:173], v[178:179], off offset:384
	global_load_dwordx4 v[174:177], v[180:181], off offset:384
	s_waitcnt lgkmcnt(7)
	v_mfma_f32_32x32x16_bf16 v[20:35], v[108:111], v[120:123], v[20:35]
	ds_write_b128 v158, v[194:197] offset:9216
	ds_write_b128 v158, v[198:201] offset:13824
	global_load_dwordx4 v[194:197], v[182:183], off offset:384
	global_load_dwordx4 v[198:201], v[184:185], off offset:384
	s_waitcnt lgkmcnt(8)
	v_mfma_f32_32x32x16_bf16 v[36:51], v[112:115], v[116:119], v[36:51]
	ds_write_b128 v158, v[230:233] offset:36864
	ds_write_b128 v158, v[240:243] offset:41472
	global_load_dwordx4 v[230:233], v[186:187], off offset:384
	global_load_dwordx4 v[240:243], v[188:189], off offset:384
	v_mfma_f32_32x32x16_bf16 v[4:19], v[112:115], v[120:123], v[4:19]
	ds_write_b128 v158, v[244:247] offset:46080
	ds_write_b128 v158, v[248:251] offset:50688
	global_load_dwordx4 v[244:247], v[190:191], off offset:384
	global_load_dwordx4 v[248:251], v[192:193], off offset:384
	ds_read_b128 v[108:111], v2 offset:64
	ds_read_b128 v[116:119], v107 offset:36928
	ds_read_b128 v[120:123], v107 offset:41536
	ds_read_b128 v[112:115], v2 offset:4672
	s_waitcnt lgkmcnt(14)
	v_mfma_f32_32x32x16_bf16 v[52:67], v[124:127], v[150:153], v[52:67]
	s_waitcnt lgkmcnt(13)
	v_mfma_f32_32x32x16_bf16 v[20:35], v[124:127], v[154:157], v[20:35]
	s_waitcnt lgkmcnt(12)
	v_mfma_f32_32x32x16_bf16 v[36:51], v[130:133], v[150:153], v[36:51]
	v_mfma_f32_32x32x16_bf16 v[4:19], v[130:133], v[154:157], v[4:19]
	ds_read_b128 v[124:127], v2 offset:96
	ds_read_b128 v[150:153], v107 offset:36960
	ds_read_b128 v[154:157], v107 offset:41568
	ds_read_b128 v[130:133], v2 offset:4704
	s_waitcnt lgkmcnt(6)
	v_mfma_f32_32x32x16_bf16 v[52:67], v[108:111], v[116:119], v[52:67]
	v_lshl_add_u64 v[178:179], v[178:179], 0, s[12:13]
	v_lshl_add_u64 v[180:181], v[180:181], 0, s[12:13]
	v_lshl_add_u64 v[182:183], v[182:183], 0, s[12:13]
	s_waitcnt lgkmcnt(5)
	v_mfma_f32_32x32x16_bf16 v[20:35], v[108:111], v[120:123], v[20:35]
	v_lshl_add_u64 v[184:185], v[184:185], 0, s[12:13]
	v_lshl_add_u64 v[186:187], v[186:187], 0, s[12:13]
	v_lshl_add_u64 v[188:189], v[188:189], 0, s[12:13]
	s_waitcnt lgkmcnt(4)
	v_mfma_f32_32x32x16_bf16 v[36:51], v[112:115], v[116:119], v[36:51]
	v_lshl_add_u64 v[190:191], v[190:191], 0, s[12:13]
	v_lshl_add_u64 v[192:193], v[192:193], 0, s[12:13]
	v_mfma_f32_32x32x16_bf16 v[4:19], v[112:115], v[120:123], v[4:19]
	s_add_i32 s36, s36, 1
	s_waitcnt lgkmcnt(0)
	s_barrier
; #define MFMA32(a, b, c) __builtin_amdgcn_mfma_f32_32x32x16_bf16((a), (b), (c), 0, 0, 0)
; #define G_LOAD(KOFF) do { rw0 = *(const uint4*)(gw + (KOFF)); rw1 = *(const uint4*)(gw1 + (KOFF)); rw2 = *(const uint4*)(gw2 + (KOFF)); rw3 = *(const uint4*)(gw3 + (KOFF)); \
;                           rx0 = *(const uint4*)(gx + (KOFF)); rx1 = *(const uint4*)(gx1 + (KOFF)); rx2 = *(const uint4*)(gx2 + (KOFF)); rx3 = *(const uint4*)(gx3 + (KOFF)); } while (0)
; DI void gemm128(const u16* __restrict__ W, int ldw, const u16* __restrict__ X, int ldx, int K, f32x16 (&acc)[2][2], char* smem) {
;     ...
;   for (int kt = 0; kt < nk; ++kt) {
;     const int buf = kt & 1;
; #pragma unroll
;     for (int ks = 0; ks < 4; ++ks) {
;       bf16x8 a0 = *(const bf16x8*)&sw[buf][wn * 64 + r][ks * 16 + h * 8];
;       bf16x8 a1 = *(const bf16x8*)&sw[buf][wn * 64 + 32 + r][ks * 16 + h * 8];
;       bf16x8 b0 = *(const bf16x8*)&sx[buf][wm * 64 + r][ks * 16 + h * 8];
;       bf16x8 b1 = *(const bf16x8*)&sx[buf][wm * 64 + 32 + r][ks * 16 + h * 8];
;       acc[0][0] = MFMA32(a0, b0, acc[0][0]);
;       acc[0][1] = MFMA32(a0, b1, acc[0][1]);
;       acc[1][0] = MFMA32(a1, b0, acc[1][0]);
;       acc[1][1] = MFMA32(a1, b1, acc[1][1]);
;     }
;     if (kt + 1 < nk) G_STORE(buf ^ 1);
;     if (kt + 2 < nk) G_LOAD((kt + 2) * 64);
;     __syncthreads();
;   }
	ds_read_b128 v[108:111], v159
	ds_read_b128 v[116:119], v160 offset:36864
	ds_read_b128 v[120:123], v160 offset:41472
	ds_read_b128 v[112:115], v159 offset:4608
	v_mfma_f32_32x32x16_bf16 v[52:67], v[124:127], v[150:153], v[52:67]
	v_mfma_f32_32x32x16_bf16 v[20:35], v[124:127], v[154:157], v[20:35]
	v_mfma_f32_32x32x16_bf16 v[36:51], v[130:133], v[150:153], v[36:51]
	v_mfma_f32_32x32x16_bf16 v[4:19], v[130:133], v[154:157], v[4:19]
	s_cmp_lt_u32 s36, 12
	s_cbranch_scc1 .Lout_kloop
	s_and_b32 s0, s36, 1
	s_mul_i32 s1, s0, 0x4800
	s_xor_b32 s0, s0, 1
	s_mulk_i32 s0, 0x4800
	v_add_u32_e32 v2, s1, v106
	v_add_u32_e32 v107, s1, v1
	v_add_u32_e32 v158, s0, v0
	v_add_u32_e32 v159, s0, v106
	v_add_u32_e32 v160, s0, v1
	ds_read_b128 v[124:127], v2 offset:32
	ds_read_b128 v[150:153], v107 offset:36896
	ds_read_b128 v[154:157], v107 offset:41504
	ds_read_b128 v[130:133], v2 offset:4640
	s_waitcnt lgkmcnt(6)
	v_mfma_f32_32x32x16_bf16 v[52:67], v[108:111], v[116:119], v[52:67]
	s_waitcnt vmcnt(8)
	ds_write_b128 v158, v[68:71]
	ds_write_b128 v158, v[72:75] offset:4608
	global_load_dwordx4 v[68:71], v[178:179], off offset:384
	global_load_dwordx4 v[72:75], v[180:181], off offset:384
	s_waitcnt lgkmcnt(7)
	v_mfma_f32_32x32x16_bf16 v[20:35], v[108:111], v[120:123], v[20:35]
	ds_write_b128 v158, v[76:79] offset:9216
	ds_write_b128 v158, v[80:83] offset:13824
	global_load_dwordx4 v[76:79], v[182:183], off offset:384
	global_load_dwordx4 v[80:83], v[184:185], off offset:384
	s_waitcnt lgkmcnt(8)
	v_mfma_f32_32x32x16_bf16 v[36:51], v[112:115], v[116:119], v[36:51]
	ds_write_b128 v158, v[84:87] offset:36864
	ds_write_b128 v158, v[88:91] offset:41472
	global_load_dwordx4 v[84:87], v[186:187], off offset:384
	global_load_dwordx4 v[88:91], v[188:189], off offset:384
	v_mfma_f32_32x32x16_bf16 v[4:19], v[112:115], v[120:123], v[4:19]
	ds_write_b128 v158, v[92:95] offset:46080
	ds_write_b128 v158, v[96:99] offset:50688
	global_load_dwordx4 v[92:95], v[190:191], off offset:384
	global_load_dwordx4 v[96:99], v[192:193], off offset:384
	ds_read_b128 v[108:111], v2 offset:64
	ds_read_b128 v[116:119], v107 offset:36928
	ds_read_b128 v[120:123], v107 offset:41536
	ds_read_b128 v[112:115], v2 offset:4672
	s_waitcnt lgkmcnt(14)
	v_mfma_f32_32x32x16_bf16 v[52:67], v[124:127], v[150:153], v[52:67]
	s_waitcnt lgkmcnt(13)
	v_mfma_f32_32x32x16_bf16 v[20:35], v[124:127], v[154:157], v[20:35]
	s_waitcnt lgkmcnt(12)
	v_mfma_f32_32x32x16_bf16 v[36:51], v[130:133], v[150:153], v[36:51]
	v_mfma_f32_32x32x16_bf16 v[4:19], v[130:133], v[154:157], v[4:19]
	ds_read_b128 v[124:127], v2 offset:96
	ds_read_b128 v[150:153], v107 offset:36960
	ds_read_b128 v[154:157], v107 offset:41568
	ds_read_b128 v[130:133], v2 offset:4704
	s_waitcnt lgkmcnt(6)
	v_mfma_f32_32x32x16_bf16 v[52:67], v[108:111], v[116:119], v[52:67]
	v_lshl_add_u64 v[178:179], v[178:179], 0, s[12:13]
	v_lshl_add_u64 v[180:181], v[180:181], 0, s[12:13]
	v_lshl_add_u64 v[182:183], v[182:183], 0, s[12:13]
	s_waitcnt lgkmcnt(5)
	v_mfma_f32_32x32x16_bf16 v[20:35], v[108:111], v[120:123], v[20:35]
	v_lshl_add_u64 v[184:185], v[184:185], 0, s[12:13]
	v_lshl_add_u64 v[186:187], v[186:187], 0, s[12:13]
	v_lshl_add_u64 v[188:189], v[188:189], 0, s[12:13]
	s_waitcnt lgkmcnt(4)
	v_mfma_f32_32x32x16_bf16 v[36:51], v[112:115], v[116:119], v[36:51]
	v_lshl_add_u64 v[190:191], v[190:191], 0, s[12:13]
	v_lshl_add_u64 v[192:193], v[192:193], 0, s[12:13]
	v_mfma_f32_32x32x16_bf16 v[4:19], v[112:115], v[120:123], v[4:19]
	s_add_i32 s36, s36, 1
	s_waitcnt lgkmcnt(0)
	s_barrier
	ds_read_b128 v[108:111], v159
	ds_read_b128 v[116:119], v160 offset:36864
	ds_read_b128 v[120:123], v160 offset:41472
	ds_read_b128 v[112:115], v159 offset:4608
	v_mfma_f32_32x32x16_bf16 v[52:67], v[124:127], v[150:153], v[52:67]
	v_mfma_f32_32x32x16_bf16 v[20:35], v[124:127], v[154:157], v[20:35]
	v_mfma_f32_32x32x16_bf16 v[36:51], v[130:133], v[150:153], v[36:51]
	v_mfma_f32_32x32x16_bf16 v[4:19], v[130:133], v[154:157], v[4:19]
	s_and_b32 s0, s36, 1
	s_mul_i32 s1, s0, 0x4800
	s_xor_b32 s0, s0, 1
	s_mulk_i32 s0, 0x4800
	v_add_u32_e32 v2, s1, v106
	v_add_u32_e32 v107, s1, v1
	v_add_u32_e32 v158, s0, v0
	v_add_u32_e32 v159, s0, v106
	v_add_u32_e32 v160, s0, v1
	ds_read_b128 v[124:127], v2 offset:32
	ds_read_b128 v[150:153], v107 offset:36896
	ds_read_b128 v[154:157], v107 offset:41504
	ds_read_b128 v[130:133], v2 offset:4640
	s_waitcnt lgkmcnt(6)
	v_mfma_f32_32x32x16_bf16 v[52:67], v[108:111], v[116:119], v[52:67]
	s_waitcnt vmcnt(8)
	ds_write_b128 v158, v[170:173]
	ds_write_b128 v158, v[174:177] offset:4608
	s_waitcnt lgkmcnt(7)
	v_mfma_f32_32x32x16_bf16 v[20:35], v[108:111], v[120:123], v[20:35]
	ds_write_b128 v158, v[194:197] offset:9216
	ds_write_b128 v158, v[198:201] offset:13824
	s_waitcnt lgkmcnt(8)
	v_mfma_f32_32x32x16_bf16 v[36:51], v[112:115], v[116:119], v[36:51]
	ds_write_b128 v158, v[230:233] offset:36864
	ds_write_b128 v158, v[240:243] offset:41472
	v_mfma_f32_32x32x16_bf16 v[4:19], v[112:115], v[120:123], v[4:19]
	ds_write_b128 v158, v[244:247] offset:46080
	ds_write_b128 v158, v[248:251] offset:50688
	ds_read_b128 v[108:111], v2 offset:64
	ds_read_b128 v[116:119], v107 offset:36928
	ds_read_b128 v[120:123], v107 offset:41536
	ds_read_b128 v[112:115], v2 offset:4672
	s_waitcnt lgkmcnt(14)
	v_mfma_f32_32x32x16_bf16 v[52:67], v[124:127], v[150:153], v[52:67]
	s_waitcnt lgkmcnt(13)
	v_mfma_f32_32x32x16_bf16 v[20:35], v[124:127], v[154:157], v[20:35]
	s_waitcnt lgkmcnt(12)
	v_mfma_f32_32x32x16_bf16 v[36:51], v[130:133], v[150:153], v[36:51]
	v_mfma_f32_32x32x16_bf16 v[4:19], v[130:133], v[154:157], v[4:19]
	ds_read_b128 v[124:127], v2 offset:96
	ds_read_b128 v[150:153], v107 offset:36960
	ds_read_b128 v[154:157], v107 offset:41568
	ds_read_b128 v[130:133], v2 offset:4704
	s_waitcnt lgkmcnt(6)
	v_mfma_f32_32x32x16_bf16 v[52:67], v[108:111], v[116:119], v[52:67]
	v_lshl_add_u64 v[178:179], v[178:179], 0, s[12:13]
	v_lshl_add_u64 v[180:181], v[180:181], 0, s[12:13]
	v_lshl_add_u64 v[182:183], v[182:183], 0, s[12:13]
	s_waitcnt lgkmcnt(5)
	v_mfma_f32_32x32x16_bf16 v[20:35], v[108:111], v[120:123], v[20:35]
	v_lshl_add_u64 v[184:185], v[184:185], 0, s[12:13]
	v_lshl_add_u64 v[186:187], v[186:187], 0, s[12:13]
	v_lshl_add_u64 v[188:189], v[188:189], 0, s[12:13]
	s_waitcnt lgkmcnt(4)
	v_mfma_f32_32x32x16_bf16 v[36:51], v[112:115], v[116:119], v[36:51]
	v_lshl_add_u64 v[190:191], v[190:191], 0, s[12:13]
	v_lshl_add_u64 v[192:193], v[192:193], 0, s[12:13]
	v_mfma_f32_32x32x16_bf16 v[4:19], v[112:115], v[120:123], v[4:19]
	s_add_i32 s36, s36, 1
	s_waitcnt lgkmcnt(0)
	s_barrier
; #define MFMA32(a, b, c) __builtin_amdgcn_mfma_f32_32x32x16_bf16((a), (b), (c), 0, 0, 0)
; #define G_LOAD(KOFF) do { rw0 = *(const uint4*)(gw + (KOFF)); rw1 = *(const uint4*)(gw1 + (KOFF)); rw2 = *(const uint4*)(gw2 + (KOFF)); rw3 = *(const uint4*)(gw3 + (KOFF)); \
;                           rx0 = *(const uint4*)(gx + (KOFF)); rx1 = *(const uint4*)(gx1 + (KOFF)); rx2 = *(const uint4*)(gx2 + (KOFF)); rx3 = *(const uint4*)(gx3 + (KOFF)); } while (0)
; DI void gemm128(const u16* __restrict__ W, int ldw, const u16* __restrict__ X, int ldx, int K, f32x16 (&acc)[2][2], char* smem) {
;     ...
;     for (int ks = 0; ks < 4; ++ks) {
;       bf16x8 a0 = *(const bf16x8*)&sw[buf][wn * 64 + r][ks * 16 + h * 8];
;       bf16x8 a1 = *(const bf16x8*)&sw[buf][wn * 64 + 32 + r][ks * 16 + h * 8];
;       bf16x8 b0 = *(const bf16x8*)&sx[buf][wm * 64 + r][ks * 16 + h * 8];
;       bf16x8 b1 = *(const bf16x8*)&sx[buf][wm * 64 + 32 + r][ks * 16 + h * 8];
;       acc[0][0] = MFMA32(a0, b0, acc[0][0]);
;       acc[0][1] = MFMA32(a0, b1, acc[0][1]);
;       acc[1][0] = MFMA32(a1, b0, acc[1][0]);
;       acc[1][1] = MFMA32(a1, b1, acc[1][1]);
;     }
;     if (kt + 1 < nk) G_STORE(buf ^ 1);
;     if (kt + 2 < nk) G_LOAD((kt + 2) * 64);
;     __syncthreads();
	v_mfma_f32_32x32x16_bf16 v[52:67], v[124:127], v[150:153], v[52:67]
	v_mfma_f32_32x32x16_bf16 v[20:35], v[124:127], v[154:157], v[20:35]
	v_mfma_f32_32x32x16_bf16 v[36:51], v[130:133], v[150:153], v[36:51]
	v_mfma_f32_32x32x16_bf16 v[4:19], v[130:133], v[154:157], v[4:19]
	ds_read_b128 v[100:103], v106 offset:4608
	ds_read_b128 v[108:111], v1 offset:41472
	ds_read_b128 v[112:115], v106
	ds_read_b128 v[116:119], v106 offset:32
	ds_read_b128 v[120:123], v1 offset:36864
	ds_read_b128 v[124:127], v1 offset:36896
	s_waitcnt lgkmcnt(4)
	v_mfma_f32_32x32x16_bf16 v[4:19], v[100:103], v[108:111], v[4:19]
	v_add_u32_e32 v2, 0xd800, v0
	s_waitcnt lgkmcnt(1)
	v_mfma_f32_32x32x16_bf16 v[52:67], v[112:115], v[120:123], v[52:67]
	v_mfma_f32_32x32x16_bf16 v[20:35], v[112:115], v[108:111], v[20:35]
	v_mfma_f32_32x32x16_bf16 v[36:51], v[100:103], v[120:123], v[36:51]
	ds_read_b128 v[100:103], v106 offset:4640
	ds_read_b128 v[108:111], v1 offset:41504
	s_waitcnt lgkmcnt(2)
	v_mfma_f32_32x32x16_bf16 v[52:67], v[116:119], v[124:127], v[52:67]
	s_waitcnt lgkmcnt(0)
	v_mfma_f32_32x32x16_bf16 v[20:35], v[116:119], v[108:111], v[20:35]
	v_mfma_f32_32x32x16_bf16 v[36:51], v[100:103], v[124:127], v[36:51]
	v_mfma_f32_32x32x16_bf16 v[4:19], v[100:103], v[108:111], v[4:19]
	ds_read_b128 v[100:103], v106 offset:64
	ds_read_b128 v[108:111], v106 offset:4672
	ds_read_b128 v[112:115], v1 offset:36928
	ds_read_b128 v[116:119], v1 offset:41536
	s_waitcnt lgkmcnt(1)
	v_mfma_f32_32x32x16_bf16 v[52:67], v[100:103], v[112:115], v[52:67]
	s_waitcnt lgkmcnt(0)
	v_mfma_f32_32x32x16_bf16 v[20:35], v[100:103], v[116:119], v[20:35]
	v_mfma_f32_32x32x16_bf16 v[36:51], v[108:111], v[112:115], v[36:51]
	v_mfma_f32_32x32x16_bf16 v[4:19], v[108:111], v[116:119], v[4:19]
	ds_read_b128 v[100:103], v106 offset:96
	ds_read_b128 v[108:111], v106 offset:4704
	ds_read_b128 v[112:115], v1 offset:36960
	ds_read_b128 v[116:119], v1 offset:41568
	s_waitcnt vmcnt(7)
	ds_write_b128 v0, v[68:71] offset:18432
	s_waitcnt vmcnt(6)
	ds_write_b128 v0, v[72:75] offset:23040
	s_waitcnt vmcnt(5)
	ds_write_b128 v0, v[76:79] offset:27648
	s_waitcnt vmcnt(4)
	ds_write_b128 v0, v[80:83] offset:32256
	s_waitcnt vmcnt(3)
	ds_write_b128 v0, v[84:87] offset:55296
	s_waitcnt vmcnt(2)
	ds_write_b128 v0, v[88:91] offset:59904
	s_waitcnt vmcnt(1)
	ds_write_b128 v0, v[92:95] offset:64512
	s_waitcnt vmcnt(0)
	ds_write_b128 v2, v[96:99] offset:13824
	s_waitcnt lgkmcnt(0)
	s_barrier
	ds_read_b128 v[68:71], v106 offset:23040
	ds_read_b128 v[72:75], v1 offset:59904
	ds_read_b128 v[76:79], v106 offset:18432
	ds_read_b128 v[80:83], v106 offset:18464
	ds_read_b128 v[84:87], v1 offset:55296
	ds_read_b128 v[88:91], v1 offset:55328
	v_mfma_f32_32x32x16_bf16 v[52:67], v[100:103], v[112:115], v[52:67]
	v_and_b32_e32 v2, 64, v213
	v_add_u32_e32 v2, 64, v2
	v_or_b32_e32 v0, s30, v105
	v_mfma_f32_32x32x16_bf16 v[20:35], v[100:103], v[116:119], v[20:35]
	v_mfma_f32_32x32x16_bf16 v[36:51], v[108:111], v[112:115], v[36:51]
	v_mfma_f32_32x32x16_bf16 v[4:19], v[108:111], v[116:119], v[4:19]
	s_waitcnt lgkmcnt(1)
	v_mfma_f32_32x32x16_bf16 v[52:67], v[76:79], v[84:87], v[52:67]
	v_mfma_f32_32x32x16_bf16 v[20:35], v[76:79], v[72:75], v[20:35]
	v_mfma_f32_32x32x16_bf16 v[36:51], v[68:71], v[84:87], v[36:51]
	v_mfma_f32_32x32x16_bf16 v[4:19], v[68:71], v[72:75], v[4:19]
	ds_read_b128 v[68:71], v106 offset:23072
	ds_read_b128 v[72:75], v1 offset:59936
	s_waitcnt lgkmcnt(2)
	v_mfma_f32_32x32x16_bf16 v[52:67], v[80:83], v[88:91], v[52:67]
	s_waitcnt lgkmcnt(0)
	v_mfma_f32_32x32x16_bf16 v[20:35], v[80:83], v[72:75], v[20:35]
	v_mfma_f32_32x32x16_bf16 v[36:51], v[68:71], v[88:91], v[36:51]
	v_mfma_f32_32x32x16_bf16 v[4:19], v[68:71], v[72:75], v[4:19]
	ds_read_b128 v[68:71], v106 offset:18496
	ds_read_b128 v[72:75], v106 offset:23104
	ds_read_b128 v[76:79], v1 offset:55360
	ds_read_b128 v[80:83], v1 offset:59968
	s_waitcnt lgkmcnt(1)
	v_mfma_f32_32x32x16_bf16 v[52:67], v[68:71], v[76:79], v[52:67]
	s_waitcnt lgkmcnt(0)
	v_mfma_f32_32x32x16_bf16 v[20:35], v[68:71], v[80:83], v[20:35]
	v_mfma_f32_32x32x16_bf16 v[36:51], v[72:75], v[76:79], v[36:51]
	v_mfma_f32_32x32x16_bf16 v[4:19], v[72:75], v[80:83], v[4:19]
	ds_read_b128 v[68:71], v106 offset:18528
	ds_read_b128 v[72:75], v106 offset:23136
	ds_read_b128 v[76:79], v1 offset:55392
	ds_read_b128 v[80:83], v1 offset:60000
	v_xor_b32_e32 v1, 32, v213
	v_cmp_lt_i32_e64 s[0:1], v1, v2
	s_waitcnt lgkmcnt(0)
	s_barrier
; DI uint32_t pack2(float a, float b) { f2_t v = {a, b}; bf2_t r = __builtin_convertvector(v, bf2_t); return __builtin_bit_cast(uint32_t, r); }
; DI float xor32(float v) { return __shfl_xor(v, 32); }
; DI void phase_out(const Params& p, int layer, char* smem, int xcd, int loc, int nloc) {
;     ...
; #pragma unroll
;     for (int mi = 0; mi < 2; ++mi) {
;       const int m = m0 + wm * 64 + mi * 32 + r;
;       float ss = 0.f;
; #pragma unroll
;       for (int ni = 0; ni < 2; ++ni)
; #pragma unroll
;         for (int g = 0; g < 4; ++g) {
;           const int n4 = n0 + wn * 64 + ni * 32 + 8 * g + 4 * h;
;           float4 xo = *(const float4*)(xin + (size_t)m * 1024 + n4);
;           xo.x += acc[ni][mi][4 * g]; xo.y += acc[ni][mi][4 * g + 1]; xo.z += acc[ni][mi][4 * g + 2]; xo.w += acc[ni][mi][4 * g + 3];
;           *(float4*)(p.out + (size_t)m * 1024 + n4) = xo;
;           *(uint2*)(XB + (size_t)m * LDX + n4) = make_uint2(pack2(xo.x, xo.y), pack2(xo.z, xo.w));
;           ss += xo.x * xo.x + xo.y * xo.y + xo.z * xo.z + xo.w * xo.w;
;         }
;       ss += xor32(ss);
;       if (h == 0) XSS[(size_t)m * 16 + nt * 2 + wn] = ss;
;     }
	v_cndmask_b32_e64 v1, v213, v1, s[0:1]
	v_lshlrev_b32_e32 v2, 2, v1
	v_mfma_f32_32x32x16_bf16 v[52:67], v[68:71], v[76:79], v[52:67]
	v_ashrrev_i32_e32 v1, 31, v0
	s_lshl_b32 s0, s29, 1
	s_ashr_i32 s1, s0, 31
	s_lshl_b64 s[0:1], s[0:1], 2
	s_add_u32 s0, s16, s0
	s_addc_u32 s1, s18, s1
	v_mfma_f32_32x32x16_bf16 v[20:35], v[68:71], v[80:83], v[20:35]
	v_add_u32_e32 v68, s31, v104
	v_ashrrev_i32_e32 v69, 31, v68
	v_mov_b64_e32 v[70:71], s[22:23]
	v_mfma_f32_32x32x16_bf16 v[36:51], v[72:75], v[76:79], v[36:51]
	v_mfma_f32_32x32x16_bf16 v[4:19], v[72:75], v[80:83], v[4:19]
	v_lshlrev_b64 v[72:73], 12, v[68:69]
	v_lshl_add_u64 v[74:75], s[10:11], 0, v[72:73]
	v_mad_i64_i32 v[80:81], s[12:13], v68, s24, v[70:71]
	v_lshlrev_b64 v[70:71], 2, v[0:1]
	v_lshl_add_u64 v[74:75], v[74:75], 0, v[70:71]
	global_load_dwordx4 v[170:173], v[74:75], off
	global_load_dwordx4 v[174:177], v[74:75], off offset:32
	global_load_dwordx4 v[178:181], v[74:75], off offset:64
	global_load_dwordx4 v[182:185], v[74:75], off offset:96
	global_load_dwordx4 v[186:189], v[74:75], off offset:128
	global_load_dwordx4 v[190:193], v[74:75], off offset:160
	global_load_dwordx4 v[194:197], v[74:75], off offset:192
	global_load_dwordx4 v[198:201], v[74:75], off offset:224
	v_lshl_add_u64 v[72:73], s[92:93], 0, v[72:73]
	v_lshl_add_u64 v[72:73], v[72:73], 0, v[70:71]
	v_lshl_add_u64 v[80:81], v[0:1], 1, v[80:81]
	s_waitcnt vmcnt(0)
	v_mov_b64_e32 v[76:77], v[170:171]
	v_mov_b64_e32 v[78:79], v[172:173]
	v_pk_add_f32 v[76:77], v[52:53], v[76:77]
	v_pk_add_f32 v[78:79], v[54:55], v[78:79]
	v_cvt_pk_bf16_f32 v52, v76, v77
	v_cvt_pk_bf16_f32 v53, v78, v79
	global_store_dwordx4 v[72:73], v[76:79], off
	global_store_dwordx2 v[80:81], v[52:53], off
	v_pk_mul_f32 v[54:55], v[76:77], v[76:77]
	v_pk_mul_f32 v[52:53], v[78:79], v[78:79]
	v_mov_b64_e32 v[76:77], v[174:175]
	v_mov_b64_e32 v[78:79], v[176:177]
	v_pk_add_f32 v[76:77], v[56:57], v[76:77]
	v_pk_add_f32 v[78:79], v[58:59], v[78:79]
	v_cvt_pk_bf16_f32 v56, v76, v77
	v_cvt_pk_bf16_f32 v57, v78, v79
	global_store_dwordx4 v[72:73], v[76:79], off offset:32
	global_store_dwordx2 v[80:81], v[56:57], off offset:16
	v_pk_mul_f32 v[58:59], v[76:77], v[76:77]
	v_pk_mul_f32 v[56:57], v[78:79], v[78:79]
	v_mov_b64_e32 v[76:77], v[178:179]
	v_mov_b64_e32 v[78:79], v[180:181]
	v_pk_add_f32 v[76:77], v[60:61], v[76:77]
	v_pk_add_f32 v[78:79], v[62:63], v[78:79]
	v_cvt_pk_bf16_f32 v60, v76, v77
	v_cvt_pk_bf16_f32 v61, v78, v79
	global_store_dwordx4 v[72:73], v[76:79], off offset:64
	global_store_dwordx2 v[80:81], v[60:61], off offset:32
	v_pk_mul_f32 v[62:63], v[76:77], v[76:77]
	v_pk_mul_f32 v[60:61], v[78:79], v[78:79]
	v_mov_b64_e32 v[76:77], v[182:183]
	v_mov_b64_e32 v[78:79], v[184:185]
	v_pk_add_f32 v[76:77], v[64:65], v[76:77]
	v_pk_add_f32 v[78:79], v[66:67], v[78:79]
	v_cvt_pk_bf16_f32 v64, v76, v77
	v_cvt_pk_bf16_f32 v65, v78, v79
	global_store_dwordx4 v[72:73], v[76:79], off offset:96
	global_store_dwordx2 v[80:81], v[64:65], off offset:48
	v_pk_mul_f32 v[66:67], v[76:77], v[76:77]
	v_pk_mul_f32 v[64:65], v[78:79], v[78:79]
	v_mov_b64_e32 v[76:77], v[186:187]
	v_mov_b64_e32 v[78:79], v[188:189]
	v_pk_add_f32 v[36:37], v[36:37], v[76:77]
	v_pk_add_f32 v[38:39], v[38:39], v[78:79]
	v_cvt_pk_bf16_f32 v76, v36, v37
	v_cvt_pk_bf16_f32 v77, v38, v39
	global_store_dwordx4 v[72:73], v[36:39], off offset:128
	global_store_dwordx2 v[80:81], v[76:77], off offset:64
	v_pk_mul_f32 v[76:77], v[36:37], v[36:37]
	v_pk_mul_f32 v[78:79], v[38:39], v[38:39]
	v_mov_b64_e32 v[36:37], v[190:191]
	v_mov_b64_e32 v[38:39], v[192:193]
	v_pk_add_f32 v[36:37], v[40:41], v[36:37]
	v_pk_add_f32 v[38:39], v[42:43], v[38:39]
	v_cvt_pk_bf16_f32 v40, v36, v37
	v_cvt_pk_bf16_f32 v41, v38, v39
	global_store_dwordx4 v[72:73], v[36:39], off offset:160
	global_store_dwordx2 v[80:81], v[40:41], off offset:80
	v_pk_mul_f32 v[40:41], v[36:37], v[36:37]
	v_pk_mul_f32 v[42:43], v[38:39], v[38:39]
	v_mov_b64_e32 v[36:37], v[194:195]
	v_mov_b64_e32 v[38:39], v[196:197]
	v_add_f32_e32 v40, v40, v41
	v_add_f32_e32 v40, v42, v40
	v_add_f32_e32 v40, v43, v40
	v_pk_add_f32 v[36:37], v[44:45], v[36:37]
	v_pk_add_f32 v[38:39], v[46:47], v[38:39]
	v_cvt_pk_bf16_f32 v44, v36, v37
	v_cvt_pk_bf16_f32 v45, v38, v39
	global_store_dwordx4 v[72:73], v[36:39], off offset:192
	global_store_dwordx2 v[80:81], v[44:45], off offset:96
	v_pk_mul_f32 v[44:45], v[36:37], v[36:37]
	v_pk_mul_f32 v[46:47], v[38:39], v[38:39]
	v_mov_b64_e32 v[36:37], v[198:199]
	v_mov_b64_e32 v[38:39], v[200:201]
	v_add_f32_e32 v41, v44, v45
	v_add_f32_e32 v41, v46, v41
	v_add_f32_e32 v41, v47, v41
	v_pk_add_f32 v[36:37], v[48:49], v[36:37]
	v_pk_add_f32 v[38:39], v[50:51], v[38:39]
	v_cvt_pk_bf16_f32 v48, v36, v37
	v_cvt_pk_bf16_f32 v49, v38, v39
	global_store_dwordx4 v[72:73], v[36:39], off offset:224
	global_store_dwordx2 v[80:81], v[48:49], off offset:112
	v_add_f32_e32 v48, v54, v55
	v_add_f32_e32 v49, v58, v59
	v_add_f32_e32 v48, v52, v48
	v_add_f32_e32 v49, v56, v49
	v_add_f32_e32 v48, v53, v48
	v_add_f32_e32 v49, v57, v49
	v_add_f32_e32 v48, v48, v49
	v_add_f32_e32 v49, v62, v63
	v_add_f32_e32 v49, v60, v49
	v_add_f32_e32 v49, v61, v49
	v_add_f32_e32 v48, v48, v49
	v_add_f32_e32 v49, v66, v67
	v_add_f32_e32 v49, v64, v49
	v_add_f32_e32 v49, v65, v49
	v_add_f32_e32 v48, v48, v49
	v_add_f32_e32 v49, v76, v77
	v_add_f32_e32 v49, v78, v49
	v_pk_mul_f32 v[36:37], v[36:37], v[36:37]
	v_add_f32_e32 v49, v79, v49
	v_pk_mul_f32 v[38:39], v[38:39], v[38:39]
	v_add_f32_e32 v48, v48, v49
	v_add_f32_e32 v36, v36, v37
	v_add_f32_e32 v40, v48, v40
	v_add_f32_e32 v36, v38, v36
	v_add_f32_e32 v40, v40, v41
	v_add_f32_e32 v36, v39, v36
	v_add_f32_e32 v36, v40, v36
	ds_bpermute_b32 v37, v2, v36
	s_and_saveexec_b64 s[12:13], vcc
	s_cbranch_execz .LBB0_1404
	v_lshlrev_b64 v[38:39], 6, v[68:69]
	v_lshl_add_u64 v[38:39], s[0:1], 0, v[38:39]
	s_waitcnt lgkmcnt(0)
	v_add_f32_e32 v36, v36, v37
	global_store_dword v[38:39], v36, off
